# mixer B softmax section: validity mask as one signed compare vs per-lane threshold (+ scalar XOR of a sense flag), shift instead of v_mul_lo, per-group constants hoisted
# speedup vs baseline: 1.0080x; 1.0026x over previous
.LBB0_138:
	s_ff1_i32_b32 s32, s84
	s_lshl_b32 s68, s85, 5
	s_lshl_b32 s68, s68, s32
	v_add_u32_e32 v4, s68, v196
	v_mov_b32_e32 v12, 0
	v_cmp_gt_i32_e64 s[68:69], 0, v4
	v_sub_u32_e32 v2, v197, v4
	v_not_b32_e32 v3, v4
	s_nop 2
	v_exp_f32_e32 v64, v64
	v_cndmask_b32_e64 v2, v2, v3, s[68:69]
	v_exp_f32_e32 v65, v65
	v_ashrrev_i32_e32 v13, s32, v2
	v_exp_f32_e32 v66, v66
	v_cmp_le_i32_e32 vcc, 0, v13
	v_exp_f32_e32 v67, v67
	s_xor_b64 vcc, vcc, s[68:69]
	v_cndmask_b32_e32 v64, 0, v64, vcc
	v_add_f32_e32 v171, v64, v171
	v_cmp_le_i32_e32 vcc, 1, v13
	v_exp_f32_e32 v68, v68
	s_xor_b64 vcc, vcc, s[68:69]
	v_cndmask_b32_e32 v65, 0, v65, vcc
	v_add_f32_e32 v12, v65, v12
	v_cmp_le_i32_e32 vcc, 2, v13
	v_exp_f32_e32 v69, v69
	s_xor_b64 vcc, vcc, s[68:69]
	v_cndmask_b32_e32 v66, 0, v66, vcc
	v_add_f32_e32 v171, v66, v171
	v_cmp_le_i32_e32 vcc, 3, v13
	v_exp_f32_e32 v70, v70
	s_xor_b64 vcc, vcc, s[68:69]
	v_cndmask_b32_e32 v67, 0, v67, vcc
	v_add_f32_e32 v12, v67, v12
	v_cmp_le_i32_e32 vcc, 8, v13
	v_exp_f32_e32 v71, v71
	s_xor_b64 vcc, vcc, s[68:69]
	v_cndmask_b32_e32 v68, 0, v68, vcc
	v_add_f32_e32 v171, v68, v171
	v_cmp_le_i32_e32 vcc, 9, v13
	v_exp_f32_e32 v72, v72
	s_xor_b64 vcc, vcc, s[68:69]
	v_cndmask_b32_e32 v69, 0, v69, vcc
	v_add_f32_e32 v12, v69, v12
	v_cmp_le_i32_e32 vcc, 10, v13
	v_exp_f32_e32 v73, v73
	s_xor_b64 vcc, vcc, s[68:69]
	v_cndmask_b32_e32 v70, 0, v70, vcc
	v_add_f32_e32 v171, v70, v171
	v_cmp_le_i32_e32 vcc, 11, v13
	v_exp_f32_e32 v74, v74
	s_xor_b64 vcc, vcc, s[68:69]
	v_cndmask_b32_e32 v71, 0, v71, vcc
	v_add_f32_e32 v12, v71, v12
	v_cmp_le_i32_e32 vcc, 16, v13
	v_exp_f32_e32 v75, v75
	s_xor_b64 vcc, vcc, s[68:69]
	v_cndmask_b32_e32 v72, 0, v72, vcc
	v_add_f32_e32 v171, v72, v171
	v_cmp_le_i32_e32 vcc, 17, v13
	v_exp_f32_e32 v76, v76
	s_xor_b64 vcc, vcc, s[68:69]
	v_cndmask_b32_e32 v73, 0, v73, vcc
	v_add_f32_e32 v12, v73, v12
	v_cmp_le_i32_e32 vcc, 18, v13
	v_exp_f32_e32 v77, v77
	s_xor_b64 vcc, vcc, s[68:69]
	v_cndmask_b32_e32 v74, 0, v74, vcc
	v_add_f32_e32 v171, v74, v171
	v_cmp_le_i32_e32 vcc, 19, v13
	v_exp_f32_e32 v78, v78
	s_xor_b64 vcc, vcc, s[68:69]
	v_cndmask_b32_e32 v75, 0, v75, vcc
	v_add_f32_e32 v12, v75, v12
	v_cmp_le_i32_e32 vcc, 24, v13
	v_exp_f32_e32 v79, v79
	s_xor_b64 vcc, vcc, s[68:69]
	v_cndmask_b32_e32 v76, 0, v76, vcc
	v_add_f32_e32 v171, v76, v171
	v_cmp_le_i32_e32 vcc, 25, v13
	s_nop 0
	s_xor_b64 vcc, vcc, s[68:69]
	v_cndmask_b32_e32 v77, 0, v77, vcc
	v_add_f32_e32 v12, v77, v12
	v_cmp_le_i32_e32 vcc, 26, v13
	s_nop 0
	s_xor_b64 vcc, vcc, s[68:69]
	v_cndmask_b32_e32 v78, 0, v78, vcc
	v_add_f32_e32 v171, v78, v171
	v_cmp_le_i32_e32 vcc, 27, v13
	s_nop 0
	s_xor_b64 vcc, vcc, s[68:69]
	v_cndmask_b32_e32 v79, 0, v79, vcc
	v_add_f32_e32 v12, v79, v12
	s_waitcnt lgkmcnt(0)
	v_cvt_pk_bf16_f32 v2, v64, v65
	v_cvt_pk_bf16_f32 v3, v66, v67
	v_cvt_pk_bf16_f32 v4, v68, v69
	v_cvt_pk_bf16_f32 v5, v70, v71
	v_cvt_pk_bf16_f32 v6, v72, v73
	v_cvt_pk_bf16_f32 v7, v74, v75
	v_cvt_pk_bf16_f32 v8, v76, v77
	v_cvt_pk_bf16_f32 v9, v78, v79
	v_add_f32_e32 v171, v171, v12
	s_nop 0
	v_mfma_f32_32x32x16_bf16 v[32:47], v[180:183], v[2:5], v[32:47]
	v_mfma_f32_32x32x16_bf16 v[32:47], v[184:187], v[6:9], v[32:47]
	v_mfma_f32_32x32x16_bf16 v[16:31], v[188:191], v[2:5], v[16:31]
	v_mfma_f32_32x32x16_bf16 v[16:31], v[192:195], v[6:9], v[16:31]

.LBB0_153:
	s_ff1_i32_b32 s32, s86
	s_cmp_lg_u32 s87, 0
	s_cbranch_scc1 .Lmyb_grp_same
	s_lshl_b32 s68, s86, 6
	v_subrev_u32_e32 v0, s68, v160
	v_add_u32_e32 v2, s68, v160
	v_max_i32_e32 v0, 0, v0
	v_min_i32_e32 v2, 0xfff, v2
	v_sub_u32_e32 v197, v2, v0
	v_add_u32_e32 v0, s68, v0
	v_sub_u32_e32 v0, v167, v0
	v_lshlrev_b32_e32 v3, s32, v170
	v_add_u32_e32 v196, v0, v3
.Lmyb_grp_same:
	s_lshl_b32 s68, s87, 5
	s_lshl_b32 s68, s68, s32
	v_add_u32_e32 v4, s68, v196
	v_mov_b32_e32 v12, 0
	v_cmp_gt_i32_e64 s[68:69], 0, v4
	v_sub_u32_e32 v2, v197, v4
	v_not_b32_e32 v3, v4
	s_nop 2
	v_exp_f32_e32 v64, v64
	v_cndmask_b32_e64 v2, v2, v3, s[68:69]
	v_exp_f32_e32 v65, v65
	v_ashrrev_i32_e32 v13, s32, v2
	v_exp_f32_e32 v66, v66
	v_cmp_le_i32_e32 vcc, 0, v13
	v_exp_f32_e32 v67, v67
	s_xor_b64 vcc, vcc, s[68:69]
	v_cndmask_b32_e32 v64, 0, v64, vcc
	v_add_f32_e32 v171, v64, v171
	v_cmp_le_i32_e32 vcc, 1, v13
	v_exp_f32_e32 v68, v68
	s_xor_b64 vcc, vcc, s[68:69]
	v_cndmask_b32_e32 v65, 0, v65, vcc
	v_add_f32_e32 v12, v65, v12
	v_cmp_le_i32_e32 vcc, 2, v13
	v_exp_f32_e32 v69, v69
	s_xor_b64 vcc, vcc, s[68:69]
	v_cndmask_b32_e32 v66, 0, v66, vcc
	v_add_f32_e32 v171, v66, v171
	v_cmp_le_i32_e32 vcc, 3, v13
	v_exp_f32_e32 v70, v70
	s_xor_b64 vcc, vcc, s[68:69]
	v_cndmask_b32_e32 v67, 0, v67, vcc
	v_add_f32_e32 v12, v67, v12
	v_cmp_le_i32_e32 vcc, 8, v13
	v_exp_f32_e32 v71, v71
	s_xor_b64 vcc, vcc, s[68:69]
	v_cndmask_b32_e32 v68, 0, v68, vcc
	v_add_f32_e32 v171, v68, v171
	v_cmp_le_i32_e32 vcc, 9, v13
	v_exp_f32_e32 v72, v72
	s_xor_b64 vcc, vcc, s[68:69]
	v_cndmask_b32_e32 v69, 0, v69, vcc
	v_add_f32_e32 v12, v69, v12
	v_cmp_le_i32_e32 vcc, 10, v13
	v_exp_f32_e32 v73, v73
	s_xor_b64 vcc, vcc, s[68:69]
	v_cndmask_b32_e32 v70, 0, v70, vcc
	v_add_f32_e32 v171, v70, v171
	v_cmp_le_i32_e32 vcc, 11, v13
	v_exp_f32_e32 v74, v74
	s_xor_b64 vcc, vcc, s[68:69]
	v_cndmask_b32_e32 v71, 0, v71, vcc
	v_add_f32_e32 v12, v71, v12
	v_cmp_le_i32_e32 vcc, 16, v13
	v_exp_f32_e32 v75, v75
	s_xor_b64 vcc, vcc, s[68:69]
	v_cndmask_b32_e32 v72, 0, v72, vcc
	v_add_f32_e32 v171, v72, v171
	v_cmp_le_i32_e32 vcc, 17, v13
	v_exp_f32_e32 v76, v76
	s_xor_b64 vcc, vcc, s[68:69]
	v_cndmask_b32_e32 v73, 0, v73, vcc
	v_add_f32_e32 v12, v73, v12
	v_cmp_le_i32_e32 vcc, 18, v13
	v_exp_f32_e32 v77, v77
	s_xor_b64 vcc, vcc, s[68:69]
	v_cndmask_b32_e32 v74, 0, v74, vcc
	v_add_f32_e32 v171, v74, v171
	v_cmp_le_i32_e32 vcc, 19, v13
	v_exp_f32_e32 v78, v78
	s_xor_b64 vcc, vcc, s[68:69]
	v_cndmask_b32_e32 v75, 0, v75, vcc
	v_add_f32_e32 v12, v75, v12
	v_cmp_le_i32_e32 vcc, 24, v13
	v_exp_f32_e32 v79, v79
	s_xor_b64 vcc, vcc, s[68:69]
	v_cndmask_b32_e32 v76, 0, v76, vcc
	v_add_f32_e32 v171, v76, v171
	v_cmp_le_i32_e32 vcc, 25, v13
	s_nop 0
	s_xor_b64 vcc, vcc, s[68:69]
	v_cndmask_b32_e32 v77, 0, v77, vcc
	v_add_f32_e32 v12, v77, v12
	v_cmp_le_i32_e32 vcc, 26, v13
	s_nop 0
	s_xor_b64 vcc, vcc, s[68:69]
	v_cndmask_b32_e32 v78, 0, v78, vcc
	v_add_f32_e32 v171, v78, v171
	v_cmp_le_i32_e32 vcc, 27, v13
	s_nop 0
	s_xor_b64 vcc, vcc, s[68:69]
	v_cndmask_b32_e32 v79, 0, v79, vcc
	v_add_f32_e32 v12, v79, v12
	s_waitcnt lgkmcnt(0)
	s_add_i32 s86, s93, 1
	v_cvt_pk_bf16_f32 v2, v64, v65
	v_cvt_pk_bf16_f32 v3, v66, v67
	v_cvt_pk_bf16_f32 v4, v68, v69
	v_cvt_pk_bf16_f32 v5, v70, v71
	v_cvt_pk_bf16_f32 v6, v72, v73
	v_cvt_pk_bf16_f32 v7, v74, v75
	v_cvt_pk_bf16_f32 v8, v76, v77
	v_cvt_pk_bf16_f32 v9, v78, v79
	v_add_f32_e32 v171, v171, v12
	s_cmp_gt_u32 s86, 32
	s_nop 0
	v_mfma_f32_32x32x16_bf16 v[32:47], v[180:183], v[2:5], v[32:47]
	v_mfma_f32_32x32x16_bf16 v[32:47], v[184:187], v[6:9], v[32:47]
	v_mfma_f32_32x32x16_bf16 v[16:31], v[188:191], v[2:5], v[16:31]
	v_mfma_f32_32x32x16_bf16 v[16:31], v[192:195], v[6:9], v[16:31]
	s_cbranch_scc1 .LBB0_139
	s_andn2_b64 vcc, exec, s[84:85]
	s_mov_b32 s84, 1
	s_cbranch_vccnz .LBB0_159
	s_cmp_gt_u32 s93, 27
	s_mov_b64 s[68:69], -1
	s_cbranch_scc0 .LBB0_157
	s_sub_i32 s85, s93, 27
	s_mov_b64 s[68:69], 0
